# rstd and residual loads hoisted in the out-projection epilogue
# baseline (speedup 1.0000x reference)
; __device__ __forceinline__ float sq4(f32x4 a) { return (a.x * a.x + a.y * a.y) + (a.z * a.z + a.w * a.w); }
; __device__ __forceinline__ u32x4 pack8(f32x4 a, f32x4 b) { u32x4 o; o.x = cvt_pk(a.x, a.y); o.y = cvt_pk(a.z, a.w); o.z = cvt_pk(b.x, b.y); o.w = cvt_pk(b.z, b.w); return o; }
; __device__ __forceinline__ float rstd_of(const float* SS, int row, float invw) { return 1.0f / sqrtf(SS[row] * invw + EPS); }
;     __device__ __forceinline__ void operator()(const f32x4 (&acc)[2][2][4][2], const pg8::Unit& u, int wr, int wc, int fr, int fq) const {
;         const int row0 = u.pm * 256 + wr * 64 + fr, col0 = u.pn * 256 + wc * 32 + 8 * fq;
; #pragma unroll
;         for (int ai = 0; ai < 2; ++ai)
; #pragma unroll
;             for (int m = 0; m < 4; ++m) {
;                 const int row = row0 + ai * 128 + m * 16; float ssq = 0.f;
;                 const float rb = rstd_of(SSB, row, 1.f / 512.f);
; #pragma unroll
;                 for (int bj = 0; bj < 2; ++bj) {
;                     const size_t idx = (size_t)row * D + col0 + bj * 128;
;                     const u32x4 w = *(const u32x4*)(X + idx);
;                     const f32x4 r0 = {bflo(w.x), bfhi(w.x), bflo(w.y), bfhi(w.y)}, r1 = {bflo(w.z), bfhi(w.z), bflo(w.w), bfhi(w.w)};
;                     const f32x4 v0 = r0 + acc[ai][bj][m][0] * rb, v1 = r1 + acc[ai][bj][m][1] * rb;
;                     ssq += sq4(v0) + sq4(v1);
;                     *(u32x4*)(X + idx) = pack8(v0, v1);
;                 }
;                 row_stat_add(SS, row, ssq, fq);
.LBB0_740:
	v_lshl_add_u32 v150, s70, 8, v149
	v_ashrrev_i32_e32 v151, 31, v150
	v_lshl_add_u64 v[152:153], v[150:151], 2, s[34:35]
	global_load_dword v1, v[152:153], off
	v_lshl_or_b32 v2, s60, 8, v161
	v_lshlrev_b64 v[154:155], 11, v[150:151]
	v_ashrrev_i32_e32 v3, 31, v2
	v_lshl_add_u64 v[154:155], s[96:97], 0, v[154:155]
	v_lshl_add_u64 v[168:169], v[2:3], 1, v[154:155]
	global_load_dwordx4 v[154:157], v[168:169], off
	global_load_dword v177, v[152:153], off offset:64
	global_load_dword v178, v[152:153], off offset:128
	global_load_dword v179, v[152:153], off offset:192
	global_load_dword v180, v[152:153], off offset:512
	global_load_dword v181, v[152:153], off offset:576
	global_load_dword v182, v[152:153], off offset:640
	global_load_dword v183, v[152:153], off offset:704
	global_load_dwordx4 v[184:187], v[168:169], off offset:256
	s_mov_b64 vcc, 0x8000
	v_lshl_add_u64 v[236:237], v[168:169], 0, vcc
	global_load_dwordx4 v[188:191], v[236:237], off
	global_load_dwordx4 v[192:195], v[236:237], off offset:256
	s_mov_b64 vcc, 0x10000
	v_lshl_add_u64 v[236:237], v[168:169], 0, vcc
	global_load_dwordx4 v[196:199], v[236:237], off
	global_load_dwordx4 v[200:203], v[236:237], off offset:256
	s_mov_b64 vcc, 0x18000
	v_lshl_add_u64 v[236:237], v[168:169], 0, vcc
	global_load_dwordx4 v[204:207], v[236:237], off
	global_load_dwordx4 v[208:211], v[236:237], off offset:256
	s_mov_b64 vcc, 0x40000
	v_lshl_add_u64 v[236:237], v[168:169], 0, vcc
	global_load_dwordx4 v[212:215], v[236:237], off
	global_load_dwordx4 v[216:219], v[236:237], off offset:256
	s_mov_b64 vcc, 0x48000
	v_lshl_add_u64 v[236:237], v[168:169], 0, vcc
	global_load_dwordx4 v[220:223], v[236:237], off
	global_load_dwordx4 v[224:227], v[236:237], off offset:256
	s_mov_b64 vcc, 0x50000
	v_lshl_add_u64 v[236:237], v[168:169], 0, vcc
	global_load_dwordx4 v[228:231], v[236:237], off
	global_load_dwordx4 v[232:235], v[236:237], off offset:256
	s_waitcnt vmcnt(0)
	v_fmamk_f32 v1, v1, 0x3b000000, v148
	v_mul_f32_e32 v165, 0x4f800000, v1
	v_cmp_gt_f32_e32 vcc, s63, v1
	v_lshlrev_b32_e32 v170, 16, v154
	s_nop 0
	v_cndmask_b32_e32 v1, v1, v165, vcc
	v_sqrt_f32_e32 v165, v1
	v_and_b32_e32 v171, 0xffff0000, v154
	v_lshlrev_b32_e32 v154, 16, v155
	v_and_b32_e32 v155, 0xffff0000, v155
	v_add_u32_e32 v167, -1, v165
	v_add_u32_e32 v174, 1, v165
	v_fma_f32 v175, -v167, v165, v1
	v_fma_f32 v176, -v174, v165, v1
	v_cmp_ge_f32_e64 s[0:1], 0, v175
	v_lshlrev_b32_e32 v172, 16, v156
	v_and_b32_e32 v173, 0xffff0000, v156
	v_cndmask_b32_e64 v165, v165, v167, s[0:1]
	v_cmp_lt_f32_e64 s[0:1], 0, v176
	v_lshlrev_b32_e32 v156, 16, v157
	v_and_b32_e32 v157, 0xffff0000, v157
	v_cndmask_b32_e64 v165, v165, v174, s[0:1]
	v_mul_f32_e32 v167, 0x37800000, v165
	v_cndmask_b32_e32 v165, v165, v167, vcc
	v_cmp_class_f32_e32 vcc, v1, v162
	s_nop 1
	v_cndmask_b32_e32 v1, v165, v1, vcc
	v_div_scale_f32 v165, s[0:1], v1, v1, 1.0
	v_rcp_f32_e32 v167, v165
	v_div_scale_f32 v174, vcc, 1.0, v1, 1.0
	v_fma_f32 v175, -v165, v167, 1.0
	v_fmac_f32_e32 v167, v175, v167
	v_mul_f32_e32 v175, v174, v167
	v_fma_f32 v176, -v165, v175, v174
	v_fmac_f32_e32 v175, v176, v167
	v_fma_f32 v165, -v165, v175, v174
	v_div_fmas_f32 v165, v165, v167, v175
	v_div_fixup_f32 v174, v165, v1, 1.0
	v_pk_fma_f32 v[154:155], v[130:131], v[174:175], v[154:155] op_sel_hi:[1,0,1]
	v_pk_fma_f32 v[170:171], v[128:129], v[174:175], v[170:171] op_sel_hi:[1,0,1]
	v_pk_fma_f32 v[156:157], v[126:127], v[174:175], v[156:157] op_sel_hi:[1,0,1]
	v_pk_fma_f32 v[172:173], v[124:125], v[174:175], v[172:173] op_sel_hi:[1,0,1]
	v_cvt_pk_bf16_f32 v124, v170, v171
	v_cvt_pk_bf16_f32 v125, v154, v155
	v_mul_f32_e32 v171, v171, v171
	v_cvt_pk_bf16_f32 v126, v172, v173
	v_cvt_pk_bf16_f32 v127, v156, v157
	s_nop 1
	v_mov_b64_e32 v[128:129], v[184:185]
	v_mov_b64_e32 v[130:131], v[186:187]
	v_mul_f32_e32 v155, v155, v155
	v_mul_f32_e32 v173, v173, v173
	v_mul_f32_e32 v157, v157, v157
	v_fmac_f32_e32 v171, v170, v170
	v_fmac_f32_e32 v155, v154, v154
	v_fmac_f32_e32 v173, v172, v172
	v_fmac_f32_e32 v157, v156, v156
	v_add_f32_e32 v154, v171, v155
	v_add_f32_e32 v155, v173, v157
	v_add_f32_e32 v170, v154, v155
	v_and_b32_e32 v165, 64, v164
	v_xor_b32_e32 v1, 16, v164
	v_add_u32_e32 v165, 64, v165
	v_cmp_lt_i32_e32 vcc, v1, v165
	v_xor_b32_e32 v167, 32, v164
	global_store_dwordx4 v[168:169], v[124:127], off
	v_cndmask_b32_e32 v1, v164, v1, vcc
	v_lshlrev_b32_e32 v1, 2, v1
	v_cmp_lt_i32_e32 vcc, v167, v165
	v_lshlrev_b32_e32 v154, 16, v128
	v_and_b32_e32 v155, 0xffff0000, v128
	v_lshlrev_b32_e32 v128, 16, v129
	v_and_b32_e32 v129, 0xffff0000, v129
	v_lshlrev_b32_e32 v156, 16, v130
	v_and_b32_e32 v157, 0xffff0000, v130
	v_lshlrev_b32_e32 v130, 16, v131
	v_and_b32_e32 v131, 0xffff0000, v131
	v_pk_fma_f32 v[122:123], v[122:123], v[174:175], v[128:129] op_sel_hi:[1,0,1]
	v_pk_fma_f32 v[120:121], v[120:121], v[174:175], v[154:155] op_sel_hi:[1,0,1]
	v_pk_fma_f32 v[128:129], v[118:119], v[174:175], v[130:131] op_sel_hi:[1,0,1]
	v_pk_fma_f32 v[130:131], v[116:117], v[174:175], v[156:157] op_sel_hi:[1,0,1]
	v_mul_f32_e32 v116, v121, v121
	v_mul_f32_e32 v117, v123, v123
	v_mul_f32_e32 v118, v131, v131
	v_mul_f32_e32 v119, v129, v129
	v_fmac_f32_e32 v116, v120, v120
	v_fmac_f32_e32 v117, v122, v122
	v_fmac_f32_e32 v118, v130, v130
	v_fmac_f32_e32 v119, v128, v128
	v_add_f32_e32 v116, v116, v117
	v_add_f32_e32 v117, v118, v119
	v_add_f32_e32 v116, v116, v117
	v_add_f32_e32 v116, v170, v116
	ds_bpermute_b32 v117, v1, v116
	v_cndmask_b32_e32 v118, v164, v167, vcc
	v_lshlrev_b32_e32 v118, 2, v118
	v_cvt_pk_bf16_f32 v120, v120, v121
	v_cvt_pk_bf16_f32 v121, v122, v123
	s_waitcnt lgkmcnt(0)
	v_add_f32_e32 v116, v116, v117
	ds_bpermute_b32 v117, v118, v116
	v_cvt_pk_bf16_f32 v122, v130, v131
	v_cvt_pk_bf16_f32 v123, v128, v129
	global_store_dwordx4 v[168:169], v[120:123], off offset:256
	s_and_saveexec_b64 s[0:1], s[40:41]
	s_cbranch_execz .LBB0_742
	v_lshl_add_u64 v[120:121], v[150:151], 2, s[44:45]
	s_waitcnt lgkmcnt(0)
	v_add_f32_e32 v116, v116, v117
	global_atomic_add_f32 v[120:121], v116, off
; __device__ __forceinline__ float sq4(f32x4 a) { return (a.x * a.x + a.y * a.y) + (a.z * a.z + a.w * a.w); }
; __device__ __forceinline__ u32x4 pack8(f32x4 a, f32x4 b) { u32x4 o; o.x = cvt_pk(a.x, a.y); o.y = cvt_pk(a.z, a.w); o.z = cvt_pk(b.x, b.y); o.w = cvt_pk(b.z, b.w); return o; }
; __device__ __forceinline__ float rstd_of(const float* SS, int row, float invw) { return 1.0f / sqrtf(SS[row] * invw + EPS); }
;     __device__ __forceinline__ void operator()(const f32x4 (&acc)[2][2][4][2], const pg8::Unit& u, int wr, int wc, int fr, int fq) const {
;     ...
;         for (int ai = 0; ai < 2; ++ai)
; #pragma unroll
;             for (int m = 0; m < 4; ++m) {
;                 const int row = row0 + ai * 128 + m * 16; float ssq = 0.f;
;                 const float rb = rstd_of(SSB, row, 1.f / 512.f);
; #pragma unroll
;                 for (int bj = 0; bj < 2; ++bj) {
;                     const size_t idx = (size_t)row * D + col0 + bj * 128;
;                     const u32x4 w = *(const u32x4*)(X + idx);
;                     const f32x4 r0 = {bflo(w.x), bfhi(w.x), bflo(w.y), bfhi(w.y)}, r1 = {bflo(w.z), bfhi(w.z), bflo(w.w), bfhi(w.w)};
;                     const f32x4 v0 = r0 + acc[ai][bj][m][0] * rb, v1 = r1 + acc[ai][bj][m][1] * rb;
;                     ssq += sq4(v0) + sq4(v1);
;                     *(u32x4*)(X + idx) = pack8(v0, v1);
;                 }
;                 row_stat_add(SS, row, ssq, fq);
;             }
.LBB0_742:
	s_or_b64 exec, exec, s[0:1]
	v_or_b32_e32 v116, 16, v150
	s_waitcnt lgkmcnt(0)
	v_ashrrev_i32_e32 v117, 31, v116
	v_lshl_add_u64 v[120:121], v[116:117], 2, s[34:35]
	s_nop 1
	v_mov_b32_e32 v119, v177
	v_lshlrev_b64 v[120:121], 11, v[116:117]
	v_lshl_add_u64 v[120:121], s[96:97], 0, v[120:121]
	v_lshl_add_u64 v[124:125], v[2:3], 1, v[120:121]
	s_nop 1
	v_mov_b64_e32 v[120:121], v[188:189]
	v_mov_b64_e32 v[122:123], v[190:191]
	v_fmamk_f32 v119, v119, 0x3b000000, v148
	v_mul_f32_e32 v126, 0x4f800000, v119
	v_cmp_gt_f32_e32 vcc, s63, v119
	v_and_b32_e32 v127, 0xffff0000, v120
	v_cndmask_b32_e32 v119, v119, v126, vcc
	v_sqrt_f32_e32 v130, v119
	v_lshlrev_b32_e32 v126, 16, v120
	v_lshlrev_b32_e32 v120, 16, v121
	v_and_b32_e32 v121, 0xffff0000, v121
	v_add_u32_e32 v131, -1, v130
	v_add_u32_e32 v151, 1, v130
	v_fma_f32 v154, -v131, v130, v119
	v_fma_f32 v155, -v151, v130, v119
	v_cmp_ge_f32_e64 s[0:1], 0, v154
	v_lshlrev_b32_e32 v128, 16, v122
	v_and_b32_e32 v129, 0xffff0000, v122
	v_cndmask_b32_e64 v130, v130, v131, s[0:1]
	v_cmp_lt_f32_e64 s[0:1], 0, v155
	v_lshlrev_b32_e32 v122, 16, v123
	v_and_b32_e32 v123, 0xffff0000, v123
	v_cndmask_b32_e64 v130, v130, v151, s[0:1]
	v_mul_f32_e32 v131, 0x37800000, v130
	v_cndmask_b32_e32 v130, v130, v131, vcc
	v_cmp_class_f32_e32 vcc, v119, v162
	s_nop 1
	v_cndmask_b32_e32 v119, v130, v119, vcc
	v_div_scale_f32 v130, s[0:1], v119, v119, 1.0
	v_rcp_f32_e32 v131, v130
	v_div_scale_f32 v151, vcc, 1.0, v119, 1.0
	v_fma_f32 v154, -v130, v131, 1.0
	v_fmac_f32_e32 v131, v154, v131
	v_mul_f32_e32 v154, v151, v131
	v_fma_f32 v155, -v130, v154, v151
	v_fmac_f32_e32 v154, v155, v131
	v_fma_f32 v130, -v130, v154, v151
	v_div_fmas_f32 v130, v130, v131, v154
	v_div_fixup_f32 v130, v130, v119, 1.0
	v_pk_fma_f32 v[120:121], v[114:115], v[130:131], v[120:121] op_sel_hi:[1,0,1]
	v_pk_fma_f32 v[126:127], v[112:113], v[130:131], v[126:127] op_sel_hi:[1,0,1]
	v_pk_fma_f32 v[122:123], v[110:111], v[130:131], v[122:123] op_sel_hi:[1,0,1]
	v_pk_fma_f32 v[128:129], v[108:109], v[130:131], v[128:129] op_sel_hi:[1,0,1]
	v_cvt_pk_bf16_f32 v108, v126, v127
	v_cvt_pk_bf16_f32 v109, v120, v121
	v_mul_f32_e32 v119, v127, v127
	v_cvt_pk_bf16_f32 v110, v128, v129
	v_cvt_pk_bf16_f32 v111, v122, v123
	s_nop 1
	v_mov_b64_e32 v[112:113], v[192:193]
	v_mov_b64_e32 v[114:115], v[194:195]
	v_mul_f32_e32 v121, v121, v121
	v_mul_f32_e32 v127, v129, v129
	v_mul_f32_e32 v123, v123, v123
	v_fmac_f32_e32 v119, v126, v126
	v_fmac_f32_e32 v121, v120, v120
	v_fmac_f32_e32 v127, v128, v128
	v_fmac_f32_e32 v123, v122, v122
	v_add_f32_e32 v119, v119, v121
	v_add_f32_e32 v120, v127, v123
	v_add_f32_e32 v119, v119, v120
	global_store_dwordx4 v[124:125], v[108:111], off
	v_lshlrev_b32_e32 v120, 16, v112
	v_and_b32_e32 v121, 0xffff0000, v112
	v_lshlrev_b32_e32 v112, 16, v113
	v_and_b32_e32 v113, 0xffff0000, v113
	v_lshlrev_b32_e32 v122, 16, v114
	v_and_b32_e32 v123, 0xffff0000, v114
	v_lshlrev_b32_e32 v114, 16, v115
	v_and_b32_e32 v115, 0xffff0000, v115
	v_pk_fma_f32 v[106:107], v[106:107], v[130:131], v[112:113] op_sel_hi:[1,0,1]
	v_pk_fma_f32 v[104:105], v[104:105], v[130:131], v[120:121] op_sel_hi:[1,0,1]
	v_pk_fma_f32 v[112:113], v[102:103], v[130:131], v[114:115] op_sel_hi:[1,0,1]
	v_pk_fma_f32 v[114:115], v[100:101], v[130:131], v[122:123] op_sel_hi:[1,0,1]
	v_mul_f32_e32 v100, v105, v105
	v_mul_f32_e32 v101, v107, v107
	v_mul_f32_e32 v102, v115, v115
	v_mul_f32_e32 v103, v113, v113
	v_fmac_f32_e32 v100, v104, v104
	v_fmac_f32_e32 v101, v106, v106
	v_fmac_f32_e32 v102, v114, v114
	v_fmac_f32_e32 v103, v112, v112
	v_add_f32_e32 v100, v100, v101
	v_add_f32_e32 v101, v102, v103
	v_add_f32_e32 v100, v100, v101
	v_add_f32_e32 v100, v119, v100
	ds_bpermute_b32 v101, v1, v100
	v_cvt_pk_bf16_f32 v102, v104, v105
	v_cvt_pk_bf16_f32 v103, v106, v107
	v_cvt_pk_bf16_f32 v104, v114, v115
	v_cvt_pk_bf16_f32 v105, v112, v113
	s_waitcnt lgkmcnt(0)
	v_add_f32_e32 v100, v100, v101
	ds_bpermute_b32 v101, v118, v100
	global_store_dwordx4 v[124:125], v[102:105], off offset:256
	s_and_saveexec_b64 s[0:1], s[40:41]
	s_cbranch_execz .LBB0_744
	v_lshl_add_u64 v[102:103], v[116:117], 2, s[44:45]
	s_waitcnt lgkmcnt(0)
	v_add_f32_e32 v100, v100, v101
	global_atomic_add_f32 v[102:103], v100, off
; __device__ __forceinline__ float sq4(f32x4 a) { return (a.x * a.x + a.y * a.y) + (a.z * a.z + a.w * a.w); }
; __device__ __forceinline__ u32x4 pack8(f32x4 a, f32x4 b) { u32x4 o; o.x = cvt_pk(a.x, a.y); o.y = cvt_pk(a.z, a.w); o.z = cvt_pk(b.x, b.y); o.w = cvt_pk(b.z, b.w); return o; }
; __device__ __forceinline__ float rstd_of(const float* SS, int row, float invw) { return 1.0f / sqrtf(SS[row] * invw + EPS); }
;     __device__ __forceinline__ void operator()(const f32x4 (&acc)[2][2][4][2], const pg8::Unit& u, int wr, int wc, int fr, int fq) const {
;     ...
;         for (int ai = 0; ai < 2; ++ai)
; #pragma unroll
;             for (int m = 0; m < 4; ++m) {
;                 const int row = row0 + ai * 128 + m * 16; float ssq = 0.f;
;                 const float rb = rstd_of(SSB, row, 1.f / 512.f);
; #pragma unroll
;                 for (int bj = 0; bj < 2; ++bj) {
;                     const size_t idx = (size_t)row * D + col0 + bj * 128;
;                     const u32x4 w = *(const u32x4*)(X + idx);
;                     const f32x4 r0 = {bflo(w.x), bfhi(w.x), bflo(w.y), bfhi(w.y)}, r1 = {bflo(w.z), bfhi(w.z), bflo(w.w), bfhi(w.w)};
;                     const f32x4 v0 = r0 + acc[ai][bj][m][0] * rb, v1 = r1 + acc[ai][bj][m][1] * rb;
;                     ssq += sq4(v0) + sq4(v1);
;                     *(u32x4*)(X + idx) = pack8(v0, v1);
;                 }
;                 row_stat_add(SS, row, ssq, fq);
;             }
.LBB0_744:
	s_or_b64 exec, exec, s[0:1]
	v_or_b32_e32 v100, 32, v150
	s_waitcnt lgkmcnt(0)
	v_ashrrev_i32_e32 v101, 31, v100
	v_lshl_add_u64 v[102:103], v[100:101], 2, s[34:35]
	s_nop 1
	v_mov_b32_e32 v108, v178
	v_lshlrev_b64 v[102:103], 11, v[100:101]
	v_lshl_add_u64 v[102:103], s[96:97], 0, v[102:103]
	v_lshl_add_u64 v[106:107], v[2:3], 1, v[102:103]
	s_nop 1
	v_mov_b64_e32 v[102:103], v[196:197]
	v_mov_b64_e32 v[104:105], v[198:199]
	v_fmamk_f32 v108, v108, 0x3b000000, v148
	v_mul_f32_e32 v109, 0x4f800000, v108
	v_cmp_gt_f32_e32 vcc, s63, v108
	v_lshlrev_b32_e32 v110, 16, v104
	v_cndmask_b32_e32 v112, v108, v109, vcc
	v_sqrt_f32_e32 v113, v112
	v_lshlrev_b32_e32 v108, 16, v102
	v_and_b32_e32 v109, 0xffff0000, v102
	v_lshlrev_b32_e32 v102, 16, v103
	v_add_u32_e32 v114, -1, v113
	v_add_u32_e32 v115, 1, v113
	v_fma_f32 v116, -v114, v113, v112
	v_fma_f32 v117, -v115, v113, v112
	v_cmp_ge_f32_e64 s[0:1], 0, v116
	v_and_b32_e32 v103, 0xffff0000, v103
	v_and_b32_e32 v111, 0xffff0000, v104
	v_cndmask_b32_e64 v113, v113, v114, s[0:1]
	v_cmp_lt_f32_e64 s[0:1], 0, v117
	v_lshlrev_b32_e32 v104, 16, v105
	v_and_b32_e32 v105, 0xffff0000, v105
	v_cndmask_b32_e64 v113, v113, v115, s[0:1]
	v_mul_f32_e32 v114, 0x37800000, v113
	v_cndmask_b32_e32 v113, v113, v114, vcc
	v_cmp_class_f32_e32 vcc, v112, v162
	s_nop 1
	v_cndmask_b32_e32 v112, v113, v112, vcc
	v_div_scale_f32 v113, s[0:1], v112, v112, 1.0
	v_rcp_f32_e32 v114, v113
	v_div_scale_f32 v115, vcc, 1.0, v112, 1.0
	v_fma_f32 v116, -v113, v114, 1.0
	v_fmac_f32_e32 v114, v116, v114
	v_mul_f32_e32 v116, v115, v114
	v_fma_f32 v117, -v113, v116, v115
	v_fmac_f32_e32 v116, v117, v114
	v_fma_f32 v113, -v113, v116, v115
	v_div_fmas_f32 v113, v113, v114, v116
	v_div_fixup_f32 v112, v113, v112, 1.0
	v_pk_fma_f32 v[102:103], v[98:99], v[112:113], v[102:103] op_sel_hi:[1,0,1]
	v_pk_fma_f32 v[108:109], v[96:97], v[112:113], v[108:109] op_sel_hi:[1,0,1]
	v_pk_fma_f32 v[104:105], v[94:95], v[112:113], v[104:105] op_sel_hi:[1,0,1]
	v_pk_fma_f32 v[110:111], v[92:93], v[112:113], v[110:111] op_sel_hi:[1,0,1]
	v_cvt_pk_bf16_f32 v92, v108, v109
	v_cvt_pk_bf16_f32 v93, v102, v103
	v_mul_f32_e32 v109, v109, v109
	v_cvt_pk_bf16_f32 v94, v110, v111
	v_cvt_pk_bf16_f32 v95, v104, v105
	s_nop 1
	v_mov_b64_e32 v[96:97], v[200:201]
	v_mov_b64_e32 v[98:99], v[202:203]
	v_mul_f32_e32 v103, v103, v103
	v_mul_f32_e32 v111, v111, v111
	v_mul_f32_e32 v105, v105, v105
	v_fmac_f32_e32 v109, v108, v108
	v_fmac_f32_e32 v103, v102, v102
	v_fmac_f32_e32 v111, v110, v110
	v_fmac_f32_e32 v105, v104, v104
	v_add_f32_e32 v102, v109, v103
	v_add_f32_e32 v103, v111, v105
	v_add_f32_e32 v108, v102, v103
	global_store_dwordx4 v[106:107], v[92:95], off
	v_lshlrev_b32_e32 v102, 16, v96
	v_and_b32_e32 v103, 0xffff0000, v96
	v_lshlrev_b32_e32 v96, 16, v97
	v_and_b32_e32 v97, 0xffff0000, v97
	v_lshlrev_b32_e32 v104, 16, v98
	v_and_b32_e32 v105, 0xffff0000, v98
	v_lshlrev_b32_e32 v98, 16, v99
	v_and_b32_e32 v99, 0xffff0000, v99
	v_pk_fma_f32 v[90:91], v[90:91], v[112:113], v[96:97] op_sel_hi:[1,0,1]
	v_pk_fma_f32 v[88:89], v[88:89], v[112:113], v[102:103] op_sel_hi:[1,0,1]
	v_pk_fma_f32 v[96:97], v[86:87], v[112:113], v[98:99] op_sel_hi:[1,0,1]
	v_pk_fma_f32 v[98:99], v[84:85], v[112:113], v[104:105] op_sel_hi:[1,0,1]
	v_mul_f32_e32 v84, v89, v89
	v_mul_f32_e32 v85, v91, v91
	v_mul_f32_e32 v86, v99, v99
	v_mul_f32_e32 v87, v97, v97
	v_fmac_f32_e32 v84, v88, v88
	v_fmac_f32_e32 v85, v90, v90
	v_fmac_f32_e32 v86, v98, v98
	v_fmac_f32_e32 v87, v96, v96
	v_add_f32_e32 v84, v84, v85
	v_add_f32_e32 v85, v86, v87
	v_add_f32_e32 v84, v84, v85
	v_add_f32_e32 v84, v108, v84
	ds_bpermute_b32 v85, v1, v84
	v_cvt_pk_bf16_f32 v86, v88, v89
	v_cvt_pk_bf16_f32 v87, v90, v91
	v_cvt_pk_bf16_f32 v88, v98, v99
	v_cvt_pk_bf16_f32 v89, v96, v97
	s_waitcnt lgkmcnt(0)
	v_add_f32_e32 v84, v84, v85
	ds_bpermute_b32 v85, v118, v84
	global_store_dwordx4 v[106:107], v[86:89], off offset:256
	s_and_saveexec_b64 s[0:1], s[40:41]
	s_cbranch_execz .LBB0_746
	v_lshl_add_u64 v[86:87], v[100:101], 2, s[44:45]
	s_waitcnt lgkmcnt(0)
	v_add_f32_e32 v84, v84, v85
	global_atomic_add_f32 v[86:87], v84, off
.LBB0_746:
	s_or_b64 exec, exec, s[0:1]
	v_or_b32_e32 v84, 48, v150
	s_waitcnt lgkmcnt(0)
	v_ashrrev_i32_e32 v85, 31, v84
	v_lshl_add_u64 v[86:87], v[84:85], 2, s[34:35]
	s_nop 1
	v_mov_b32_e32 v92, v179
	v_lshlrev_b64 v[86:87], 11, v[84:85]
	v_lshl_add_u64 v[86:87], s[96:97], 0, v[86:87]
	v_lshl_add_u64 v[90:91], v[2:3], 1, v[86:87]
	s_nop 1
	v_mov_b64_e32 v[86:87], v[204:205]
	v_mov_b64_e32 v[88:89], v[206:207]
	v_fmamk_f32 v92, v92, 0x3b000000, v148
	v_mul_f32_e32 v93, 0x4f800000, v92
	v_cmp_gt_f32_e32 vcc, s63, v92
	v_lshlrev_b32_e32 v94, 16, v88
	v_cndmask_b32_e32 v96, v92, v93, vcc
	v_sqrt_f32_e32 v97, v96
	v_lshlrev_b32_e32 v92, 16, v86
	v_and_b32_e32 v93, 0xffff0000, v86
	v_lshlrev_b32_e32 v86, 16, v87
	v_add_u32_e32 v98, -1, v97
	v_add_u32_e32 v99, 1, v97
	v_fma_f32 v100, -v98, v97, v96
	v_fma_f32 v101, -v99, v97, v96
	v_cmp_ge_f32_e64 s[0:1], 0, v100
	v_and_b32_e32 v87, 0xffff0000, v87
	v_and_b32_e32 v95, 0xffff0000, v88
	v_cndmask_b32_e64 v97, v97, v98, s[0:1]
	v_cmp_lt_f32_e64 s[0:1], 0, v101
	v_lshlrev_b32_e32 v88, 16, v89
	v_and_b32_e32 v89, 0xffff0000, v89
	v_cndmask_b32_e64 v97, v97, v99, s[0:1]
	v_mul_f32_e32 v98, 0x37800000, v97
	v_cndmask_b32_e32 v97, v97, v98, vcc
	v_cmp_class_f32_e32 vcc, v96, v162
	s_nop 1
	v_cndmask_b32_e32 v96, v97, v96, vcc
	v_div_scale_f32 v97, s[0:1], v96, v96, 1.0
	v_rcp_f32_e32 v98, v97
	v_div_scale_f32 v99, vcc, 1.0, v96, 1.0
	v_fma_f32 v100, -v97, v98, 1.0
	v_fmac_f32_e32 v98, v100, v98
	v_mul_f32_e32 v100, v99, v98
	v_fma_f32 v101, -v97, v100, v99
; __device__ __forceinline__ float sq4(f32x4 a) { return (a.x * a.x + a.y * a.y) + (a.z * a.z + a.w * a.w); }
; __device__ __forceinline__ u32x4 pack8(f32x4 a, f32x4 b) { u32x4 o; o.x = cvt_pk(a.x, a.y); o.y = cvt_pk(a.z, a.w); o.z = cvt_pk(b.x, b.y); o.w = cvt_pk(b.z, b.w); return o; }
; __device__ __forceinline__ float rstd_of(const float* SS, int row, float invw) { return 1.0f / sqrtf(SS[row] * invw + EPS); }
;     __device__ __forceinline__ void operator()(const f32x4 (&acc)[2][2][4][2], const pg8::Unit& u, int wr, int wc, int fr, int fq) const {
;     ...
;         for (int ai = 0; ai < 2; ++ai)
; #pragma unroll
;             for (int m = 0; m < 4; ++m) {
;                 const int row = row0 + ai * 128 + m * 16; float ssq = 0.f;
;                 const float rb = rstd_of(SSB, row, 1.f / 512.f);
; #pragma unroll
;                 for (int bj = 0; bj < 2; ++bj) {
;                     const size_t idx = (size_t)row * D + col0 + bj * 128;
;                     const u32x4 w = *(const u32x4*)(X + idx);
;                     const f32x4 r0 = {bflo(w.x), bfhi(w.x), bflo(w.y), bfhi(w.y)}, r1 = {bflo(w.z), bfhi(w.z), bflo(w.w), bfhi(w.w)};
;                     const f32x4 v0 = r0 + acc[ai][bj][m][0] * rb, v1 = r1 + acc[ai][bj][m][1] * rb;
;                     ssq += sq4(v0) + sq4(v1);
;                     *(u32x4*)(X + idx) = pack8(v0, v1);
;                 }
;                 row_stat_add(SS, row, ssq, fq);
;             }
	v_fmac_f32_e32 v100, v101, v98
	v_fma_f32 v97, -v97, v100, v99
	v_div_fmas_f32 v97, v97, v98, v100
	v_div_fixup_f32 v96, v97, v96, 1.0
	v_pk_fma_f32 v[86:87], v[82:83], v[96:97], v[86:87] op_sel_hi:[1,0,1]
	v_pk_fma_f32 v[92:93], v[80:81], v[96:97], v[92:93] op_sel_hi:[1,0,1]
	v_pk_fma_f32 v[88:89], v[78:79], v[96:97], v[88:89] op_sel_hi:[1,0,1]
	v_pk_fma_f32 v[94:95], v[76:77], v[96:97], v[94:95] op_sel_hi:[1,0,1]
	v_cvt_pk_bf16_f32 v76, v92, v93
	v_cvt_pk_bf16_f32 v77, v86, v87
	v_mul_f32_e32 v93, v93, v93
	v_cvt_pk_bf16_f32 v78, v94, v95
	v_cvt_pk_bf16_f32 v79, v88, v89
	s_nop 1
	v_mov_b64_e32 v[80:81], v[208:209]
	v_mov_b64_e32 v[82:83], v[210:211]
	v_mul_f32_e32 v87, v87, v87
	v_mul_f32_e32 v95, v95, v95
	v_mul_f32_e32 v89, v89, v89
	v_fmac_f32_e32 v93, v92, v92
	v_fmac_f32_e32 v87, v86, v86
	v_fmac_f32_e32 v95, v94, v94
	v_fmac_f32_e32 v89, v88, v88
	v_add_f32_e32 v86, v93, v87
	v_add_f32_e32 v87, v95, v89
	v_add_f32_e32 v92, v86, v87
	global_store_dwordx4 v[90:91], v[76:79], off
	v_lshlrev_b32_e32 v86, 16, v80
	v_and_b32_e32 v87, 0xffff0000, v80
	v_lshlrev_b32_e32 v80, 16, v81
	v_and_b32_e32 v81, 0xffff0000, v81
	v_lshlrev_b32_e32 v88, 16, v82
	v_and_b32_e32 v89, 0xffff0000, v82
	v_lshlrev_b32_e32 v82, 16, v83
	v_and_b32_e32 v83, 0xffff0000, v83
	v_pk_fma_f32 v[74:75], v[74:75], v[96:97], v[80:81] op_sel_hi:[1,0,1]
	v_pk_fma_f32 v[72:73], v[72:73], v[96:97], v[86:87] op_sel_hi:[1,0,1]
	v_pk_fma_f32 v[80:81], v[70:71], v[96:97], v[82:83] op_sel_hi:[1,0,1]
	v_pk_fma_f32 v[82:83], v[68:69], v[96:97], v[88:89] op_sel_hi:[1,0,1]
	v_mul_f32_e32 v68, v73, v73
	v_mul_f32_e32 v69, v75, v75
	v_mul_f32_e32 v70, v83, v83
	v_mul_f32_e32 v71, v81, v81
	v_fmac_f32_e32 v68, v72, v72
	v_fmac_f32_e32 v69, v74, v74
	v_fmac_f32_e32 v70, v82, v82
	v_fmac_f32_e32 v71, v80, v80
	v_add_f32_e32 v68, v68, v69
	v_add_f32_e32 v69, v70, v71
	v_add_f32_e32 v68, v68, v69
	v_add_f32_e32 v68, v92, v68
	ds_bpermute_b32 v69, v1, v68
	v_cvt_pk_bf16_f32 v70, v72, v73
	v_cvt_pk_bf16_f32 v71, v74, v75
	v_cvt_pk_bf16_f32 v72, v82, v83
	v_cvt_pk_bf16_f32 v73, v80, v81
	s_waitcnt lgkmcnt(0)
	v_add_f32_e32 v68, v68, v69
	ds_bpermute_b32 v69, v118, v68
	global_store_dwordx4 v[90:91], v[70:73], off offset:256
	s_and_saveexec_b64 s[0:1], s[40:41]
	s_cbranch_execz .LBB0_748
	v_lshl_add_u64 v[70:71], v[84:85], 2, s[44:45]
	s_waitcnt lgkmcnt(0)
	v_add_f32_e32 v68, v68, v69
	global_atomic_add_f32 v[70:71], v68, off
.LBB0_748:
	s_or_b64 exec, exec, s[0:1]
	s_nop 1
	v_mov_b32_e32 v76, v180
	v_add_u32_e32 v68, 0x80, v150
	s_waitcnt lgkmcnt(0)
	v_ashrrev_i32_e32 v69, 31, v68
	v_lshlrev_b64 v[70:71], 11, v[68:69]
	v_lshl_add_u64 v[70:71], s[96:97], 0, v[70:71]
	v_lshl_add_u64 v[74:75], v[2:3], 1, v[70:71]
	s_nop 1
	v_mov_b64_e32 v[70:71], v[212:213]
	v_mov_b64_e32 v[72:73], v[214:215]
	v_fmamk_f32 v76, v76, 0x3b000000, v148
	v_mul_f32_e32 v77, 0x4f800000, v76
	v_cmp_gt_f32_e32 vcc, s63, v76
	v_lshlrev_b32_e32 v78, 16, v72
	v_cndmask_b32_e32 v80, v76, v77, vcc
	v_sqrt_f32_e32 v81, v80
	v_lshlrev_b32_e32 v76, 16, v70
	v_and_b32_e32 v77, 0xffff0000, v70
	v_lshlrev_b32_e32 v70, 16, v71
	v_add_u32_e32 v82, -1, v81
	v_add_u32_e32 v83, 1, v81
	v_fma_f32 v84, -v82, v81, v80
	v_fma_f32 v85, -v83, v81, v80
	v_cmp_ge_f32_e64 s[0:1], 0, v84
	v_and_b32_e32 v71, 0xffff0000, v71
	v_and_b32_e32 v79, 0xffff0000, v72
	v_cndmask_b32_e64 v81, v81, v82, s[0:1]
	v_cmp_lt_f32_e64 s[0:1], 0, v85
	v_lshlrev_b32_e32 v72, 16, v73
	v_and_b32_e32 v73, 0xffff0000, v73
	v_cndmask_b32_e64 v81, v81, v83, s[0:1]
	v_mul_f32_e32 v82, 0x37800000, v81
	v_cndmask_b32_e32 v81, v81, v82, vcc
	v_cmp_class_f32_e32 vcc, v80, v162
	s_nop 1
	v_cndmask_b32_e32 v80, v81, v80, vcc
	v_div_scale_f32 v81, s[0:1], v80, v80, 1.0
	v_rcp_f32_e32 v82, v81
	v_div_scale_f32 v83, vcc, 1.0, v80, 1.0
	v_fma_f32 v84, -v81, v82, 1.0
	v_fmac_f32_e32 v82, v84, v82
	v_mul_f32_e32 v84, v83, v82
	v_fma_f32 v85, -v81, v84, v83
	v_fmac_f32_e32 v84, v85, v82
	v_fma_f32 v81, -v81, v84, v83
	v_div_fmas_f32 v81, v81, v82, v84
	v_div_fixup_f32 v80, v81, v80, 1.0
	v_pk_fma_f32 v[70:71], v[66:67], v[80:81], v[70:71] op_sel_hi:[1,0,1]
	v_pk_fma_f32 v[76:77], v[64:65], v[80:81], v[76:77] op_sel_hi:[1,0,1]
	v_pk_fma_f32 v[72:73], v[62:63], v[80:81], v[72:73] op_sel_hi:[1,0,1]
	v_pk_fma_f32 v[78:79], v[60:61], v[80:81], v[78:79] op_sel_hi:[1,0,1]
	v_cvt_pk_bf16_f32 v60, v76, v77
	v_cvt_pk_bf16_f32 v61, v70, v71
	v_mul_f32_e32 v77, v77, v77
	v_cvt_pk_bf16_f32 v62, v78, v79
	v_cvt_pk_bf16_f32 v63, v72, v73
	s_nop 1
	v_mov_b64_e32 v[64:65], v[216:217]
	v_mov_b64_e32 v[66:67], v[218:219]
	v_mul_f32_e32 v71, v71, v71
	v_mul_f32_e32 v79, v79, v79
	v_mul_f32_e32 v73, v73, v73
	v_fmac_f32_e32 v77, v76, v76
	v_fmac_f32_e32 v71, v70, v70
	v_fmac_f32_e32 v79, v78, v78
	v_fmac_f32_e32 v73, v72, v72
	v_add_f32_e32 v70, v77, v71
	v_add_f32_e32 v71, v79, v73
	v_add_f32_e32 v76, v70, v71
	global_store_dwordx4 v[74:75], v[60:63], off
	v_lshlrev_b32_e32 v70, 16, v64
	v_and_b32_e32 v71, 0xffff0000, v64
	v_lshlrev_b32_e32 v64, 16, v65
	v_and_b32_e32 v65, 0xffff0000, v65
	v_lshlrev_b32_e32 v72, 16, v66
	v_and_b32_e32 v73, 0xffff0000, v66
	v_lshlrev_b32_e32 v66, 16, v67
	v_and_b32_e32 v67, 0xffff0000, v67
	v_pk_fma_f32 v[58:59], v[58:59], v[80:81], v[64:65] op_sel_hi:[1,0,1]
	v_pk_fma_f32 v[56:57], v[56:57], v[80:81], v[70:71] op_sel_hi:[1,0,1]
	v_pk_fma_f32 v[64:65], v[54:55], v[80:81], v[66:67] op_sel_hi:[1,0,1]
	v_pk_fma_f32 v[66:67], v[52:53], v[80:81], v[72:73] op_sel_hi:[1,0,1]
	v_mul_f32_e32 v52, v57, v57
	v_mul_f32_e32 v53, v59, v59
	v_mul_f32_e32 v54, v67, v67
	v_mul_f32_e32 v55, v65, v65
	v_fmac_f32_e32 v52, v56, v56
	v_fmac_f32_e32 v53, v58, v58
	v_fmac_f32_e32 v54, v66, v66
	v_fmac_f32_e32 v55, v64, v64
	v_add_f32_e32 v52, v52, v53
	v_add_f32_e32 v53, v54, v55
	v_add_f32_e32 v52, v52, v53
	v_add_f32_e32 v52, v76, v52
	ds_bpermute_b32 v53, v1, v52
	v_cvt_pk_bf16_f32 v54, v56, v57
	v_cvt_pk_bf16_f32 v55, v58, v59
	v_cvt_pk_bf16_f32 v56, v66, v67
	v_cvt_pk_bf16_f32 v57, v64, v65
	s_waitcnt lgkmcnt(0)
	v_add_f32_e32 v52, v52, v53
	ds_bpermute_b32 v53, v118, v52
	global_store_dwordx4 v[74:75], v[54:57], off offset:256
	s_and_saveexec_b64 s[0:1], s[40:41]
	s_cbranch_execz .LBB0_750
	v_lshl_add_u64 v[54:55], v[68:69], 2, s[44:45]
	s_waitcnt lgkmcnt(0)
	v_add_f32_e32 v52, v52, v53
	global_atomic_add_f32 v[54:55], v52, off
; __device__ __forceinline__ float sq4(f32x4 a) { return (a.x * a.x + a.y * a.y) + (a.z * a.z + a.w * a.w); }
; __device__ __forceinline__ u32x4 pack8(f32x4 a, f32x4 b) { u32x4 o; o.x = cvt_pk(a.x, a.y); o.y = cvt_pk(a.z, a.w); o.z = cvt_pk(b.x, b.y); o.w = cvt_pk(b.z, b.w); return o; }
; __device__ __forceinline__ float rstd_of(const float* SS, int row, float invw) { return 1.0f / sqrtf(SS[row] * invw + EPS); }
;     __device__ __forceinline__ void operator()(const f32x4 (&acc)[2][2][4][2], const pg8::Unit& u, int wr, int wc, int fr, int fq) const {
;     ...
;         for (int ai = 0; ai < 2; ++ai)
; #pragma unroll
;             for (int m = 0; m < 4; ++m) {
;                 const int row = row0 + ai * 128 + m * 16; float ssq = 0.f;
;                 const float rb = rstd_of(SSB, row, 1.f / 512.f);
; #pragma unroll
;                 for (int bj = 0; bj < 2; ++bj) {
;                     const size_t idx = (size_t)row * D + col0 + bj * 128;
;                     const u32x4 w = *(const u32x4*)(X + idx);
;                     const f32x4 r0 = {bflo(w.x), bfhi(w.x), bflo(w.y), bfhi(w.y)}, r1 = {bflo(w.z), bfhi(w.z), bflo(w.w), bfhi(w.w)};
;                     const f32x4 v0 = r0 + acc[ai][bj][m][0] * rb, v1 = r1 + acc[ai][bj][m][1] * rb;
;                     ssq += sq4(v0) + sq4(v1);
;                     *(u32x4*)(X + idx) = pack8(v0, v1);
;                 }
;                 row_stat_add(SS, row, ssq, fq);
;             }
.LBB0_750:
	s_or_b64 exec, exec, s[0:1]
	s_nop 1
	v_mov_b32_e32 v60, v181
	v_add_u32_e32 v52, 0x90, v150
	s_waitcnt lgkmcnt(0)
	v_ashrrev_i32_e32 v53, 31, v52
	v_lshlrev_b64 v[54:55], 11, v[52:53]
	v_lshl_add_u64 v[54:55], s[96:97], 0, v[54:55]
	v_lshl_add_u64 v[58:59], v[2:3], 1, v[54:55]
	s_nop 1
	v_mov_b64_e32 v[54:55], v[220:221]
	v_mov_b64_e32 v[56:57], v[222:223]
	v_fmamk_f32 v60, v60, 0x3b000000, v148
	v_mul_f32_e32 v61, 0x4f800000, v60
	v_cmp_gt_f32_e32 vcc, s63, v60
	v_lshlrev_b32_e32 v62, 16, v56
	v_cndmask_b32_e32 v64, v60, v61, vcc
	v_sqrt_f32_e32 v65, v64
	v_lshlrev_b32_e32 v60, 16, v54
	v_and_b32_e32 v61, 0xffff0000, v54
	v_lshlrev_b32_e32 v54, 16, v55
	v_add_u32_e32 v66, -1, v65
	v_add_u32_e32 v67, 1, v65
	v_fma_f32 v68, -v66, v65, v64
	v_fma_f32 v69, -v67, v65, v64
	v_cmp_ge_f32_e64 s[0:1], 0, v68
	v_and_b32_e32 v55, 0xffff0000, v55
	v_and_b32_e32 v63, 0xffff0000, v56
	v_cndmask_b32_e64 v65, v65, v66, s[0:1]
	v_cmp_lt_f32_e64 s[0:1], 0, v69
	v_lshlrev_b32_e32 v56, 16, v57
	v_and_b32_e32 v57, 0xffff0000, v57
	v_cndmask_b32_e64 v65, v65, v67, s[0:1]
	v_mul_f32_e32 v66, 0x37800000, v65
	v_cndmask_b32_e32 v65, v65, v66, vcc
	v_cmp_class_f32_e32 vcc, v64, v162
	s_nop 1
	v_cndmask_b32_e32 v64, v65, v64, vcc
	v_div_scale_f32 v65, s[0:1], v64, v64, 1.0
	v_rcp_f32_e32 v66, v65
	v_div_scale_f32 v67, vcc, 1.0, v64, 1.0
	v_fma_f32 v68, -v65, v66, 1.0
	v_fmac_f32_e32 v66, v68, v66
	v_mul_f32_e32 v68, v67, v66
	v_fma_f32 v69, -v65, v68, v67
	v_fmac_f32_e32 v68, v69, v66
	v_fma_f32 v65, -v65, v68, v67
	v_div_fmas_f32 v65, v65, v66, v68
	v_div_fixup_f32 v64, v65, v64, 1.0
	v_pk_fma_f32 v[54:55], v[50:51], v[64:65], v[54:55] op_sel_hi:[1,0,1]
	v_pk_fma_f32 v[60:61], v[48:49], v[64:65], v[60:61] op_sel_hi:[1,0,1]
	v_pk_fma_f32 v[56:57], v[46:47], v[64:65], v[56:57] op_sel_hi:[1,0,1]
	v_pk_fma_f32 v[62:63], v[44:45], v[64:65], v[62:63] op_sel_hi:[1,0,1]
	v_cvt_pk_bf16_f32 v44, v60, v61
	v_cvt_pk_bf16_f32 v45, v54, v55
	v_mul_f32_e32 v61, v61, v61
	v_cvt_pk_bf16_f32 v46, v62, v63
	v_cvt_pk_bf16_f32 v47, v56, v57
	s_nop 1
	v_mov_b64_e32 v[48:49], v[224:225]
	v_mov_b64_e32 v[50:51], v[226:227]
	v_mul_f32_e32 v55, v55, v55
	v_mul_f32_e32 v63, v63, v63
	v_mul_f32_e32 v57, v57, v57
	v_fmac_f32_e32 v61, v60, v60
	v_fmac_f32_e32 v55, v54, v54
	v_fmac_f32_e32 v63, v62, v62
	v_fmac_f32_e32 v57, v56, v56
	v_add_f32_e32 v54, v61, v55
	v_add_f32_e32 v55, v63, v57
	v_add_f32_e32 v60, v54, v55
	global_store_dwordx4 v[58:59], v[44:47], off
	v_lshlrev_b32_e32 v54, 16, v48
	v_and_b32_e32 v55, 0xffff0000, v48
	v_lshlrev_b32_e32 v48, 16, v49
	v_and_b32_e32 v49, 0xffff0000, v49
	v_lshlrev_b32_e32 v56, 16, v50
	v_and_b32_e32 v57, 0xffff0000, v50
	v_lshlrev_b32_e32 v50, 16, v51
	v_and_b32_e32 v51, 0xffff0000, v51
	v_pk_fma_f32 v[42:43], v[42:43], v[64:65], v[48:49] op_sel_hi:[1,0,1]
	v_pk_fma_f32 v[40:41], v[40:41], v[64:65], v[54:55] op_sel_hi:[1,0,1]
	v_pk_fma_f32 v[48:49], v[38:39], v[64:65], v[50:51] op_sel_hi:[1,0,1]
	v_pk_fma_f32 v[50:51], v[36:37], v[64:65], v[56:57] op_sel_hi:[1,0,1]
	v_mul_f32_e32 v36, v41, v41
	v_mul_f32_e32 v37, v43, v43
	v_mul_f32_e32 v38, v51, v51
	v_mul_f32_e32 v39, v49, v49
	v_fmac_f32_e32 v36, v40, v40
	v_fmac_f32_e32 v37, v42, v42
	v_fmac_f32_e32 v38, v50, v50
	v_fmac_f32_e32 v39, v48, v48
	v_add_f32_e32 v36, v36, v37
	v_add_f32_e32 v37, v38, v39
	v_add_f32_e32 v36, v36, v37
	v_add_f32_e32 v36, v60, v36
	ds_bpermute_b32 v37, v1, v36
	v_cvt_pk_bf16_f32 v38, v40, v41
	v_cvt_pk_bf16_f32 v39, v42, v43
	v_cvt_pk_bf16_f32 v40, v50, v51
	v_cvt_pk_bf16_f32 v41, v48, v49
	s_waitcnt lgkmcnt(0)
	v_add_f32_e32 v36, v36, v37
	ds_bpermute_b32 v37, v118, v36
	global_store_dwordx4 v[58:59], v[38:41], off offset:256
	s_and_saveexec_b64 s[0:1], s[40:41]
	s_cbranch_execz .LBB0_752
	v_lshl_add_u64 v[38:39], v[52:53], 2, s[44:45]
	s_waitcnt lgkmcnt(0)
	v_add_f32_e32 v36, v36, v37
	global_atomic_add_f32 v[38:39], v36, off
.LBB0_752:
	s_or_b64 exec, exec, s[0:1]
	s_nop 1
	v_mov_b32_e32 v44, v182
	v_add_u32_e32 v36, 0xa0, v150
	s_waitcnt lgkmcnt(0)
	v_ashrrev_i32_e32 v37, 31, v36
	v_lshlrev_b64 v[38:39], 11, v[36:37]
	v_lshl_add_u64 v[38:39], s[96:97], 0, v[38:39]
	v_lshl_add_u64 v[42:43], v[2:3], 1, v[38:39]
	s_nop 1
	v_mov_b64_e32 v[38:39], v[228:229]
	v_mov_b64_e32 v[40:41], v[230:231]
	v_fmamk_f32 v44, v44, 0x3b000000, v148
	v_mul_f32_e32 v45, 0x4f800000, v44
	v_cmp_gt_f32_e32 vcc, s63, v44
	v_lshlrev_b32_e32 v46, 16, v40
	v_cndmask_b32_e32 v48, v44, v45, vcc
	v_sqrt_f32_e32 v49, v48
	v_lshlrev_b32_e32 v44, 16, v38
	v_and_b32_e32 v45, 0xffff0000, v38
	v_lshlrev_b32_e32 v38, 16, v39
	v_add_u32_e32 v50, -1, v49
	v_add_u32_e32 v51, 1, v49
	v_fma_f32 v52, -v50, v49, v48
	v_fma_f32 v53, -v51, v49, v48
	v_cmp_ge_f32_e64 s[0:1], 0, v52
	v_and_b32_e32 v39, 0xffff0000, v39
	v_and_b32_e32 v47, 0xffff0000, v40
	v_cndmask_b32_e64 v49, v49, v50, s[0:1]
	v_cmp_lt_f32_e64 s[0:1], 0, v53
	v_lshlrev_b32_e32 v40, 16, v41
	v_and_b32_e32 v41, 0xffff0000, v41
	v_cndmask_b32_e64 v49, v49, v51, s[0:1]
	v_mul_f32_e32 v50, 0x37800000, v49
	v_cndmask_b32_e32 v49, v49, v50, vcc
	v_cmp_class_f32_e32 vcc, v48, v162
	s_nop 1
	v_cndmask_b32_e32 v48, v49, v48, vcc
	v_div_scale_f32 v49, s[0:1], v48, v48, 1.0
	v_rcp_f32_e32 v50, v49
	v_div_scale_f32 v51, vcc, 1.0, v48, 1.0
	v_fma_f32 v52, -v49, v50, 1.0
	v_fmac_f32_e32 v50, v52, v50
	v_mul_f32_e32 v52, v51, v50
	v_fma_f32 v53, -v49, v52, v51
	v_fmac_f32_e32 v52, v53, v50
	v_fma_f32 v49, -v49, v52, v51
	v_div_fmas_f32 v49, v49, v50, v52
	v_div_fixup_f32 v48, v49, v48, 1.0
	v_pk_fma_f32 v[38:39], v[34:35], v[48:49], v[38:39] op_sel_hi:[1,0,1]
	v_pk_fma_f32 v[44:45], v[32:33], v[48:49], v[44:45] op_sel_hi:[1,0,1]
; __device__ __forceinline__ float sq4(f32x4 a) { return (a.x * a.x + a.y * a.y) + (a.z * a.z + a.w * a.w); }
; __device__ __forceinline__ u32x4 pack8(f32x4 a, f32x4 b) { u32x4 o; o.x = cvt_pk(a.x, a.y); o.y = cvt_pk(a.z, a.w); o.z = cvt_pk(b.x, b.y); o.w = cvt_pk(b.z, b.w); return o; }
; __device__ __forceinline__ float rstd_of(const float* SS, int row, float invw) { return 1.0f / sqrtf(SS[row] * invw + EPS); }
;     __device__ __forceinline__ void operator()(const f32x4 (&acc)[2][2][4][2], const pg8::Unit& u, int wr, int wc, int fr, int fq) const {
;     ...
;         for (int ai = 0; ai < 2; ++ai)
; #pragma unroll
;             for (int m = 0; m < 4; ++m) {
;                 const int row = row0 + ai * 128 + m * 16; float ssq = 0.f;
;                 const float rb = rstd_of(SSB, row, 1.f / 512.f);
; #pragma unroll
;                 for (int bj = 0; bj < 2; ++bj) {
;                     const size_t idx = (size_t)row * D + col0 + bj * 128;
;                     const u32x4 w = *(const u32x4*)(X + idx);
;                     const f32x4 r0 = {bflo(w.x), bfhi(w.x), bflo(w.y), bfhi(w.y)}, r1 = {bflo(w.z), bfhi(w.z), bflo(w.w), bfhi(w.w)};
;                     const f32x4 v0 = r0 + acc[ai][bj][m][0] * rb, v1 = r1 + acc[ai][bj][m][1] * rb;
;                     ssq += sq4(v0) + sq4(v1);
;                     *(u32x4*)(X + idx) = pack8(v0, v1);
;                 }
;                 row_stat_add(SS, row, ssq, fq);
;             }
	v_pk_fma_f32 v[40:41], v[30:31], v[48:49], v[40:41] op_sel_hi:[1,0,1]
	v_pk_fma_f32 v[46:47], v[28:29], v[48:49], v[46:47] op_sel_hi:[1,0,1]
	v_cvt_pk_bf16_f32 v28, v44, v45
	v_cvt_pk_bf16_f32 v29, v38, v39
	v_mul_f32_e32 v45, v45, v45
	v_cvt_pk_bf16_f32 v30, v46, v47
	v_cvt_pk_bf16_f32 v31, v40, v41
	s_nop 1
	v_mov_b64_e32 v[32:33], v[232:233]
	v_mov_b64_e32 v[34:35], v[234:235]
	v_mul_f32_e32 v39, v39, v39
	v_mul_f32_e32 v47, v47, v47
	v_mul_f32_e32 v41, v41, v41
	v_fmac_f32_e32 v45, v44, v44
	v_fmac_f32_e32 v39, v38, v38
	v_fmac_f32_e32 v47, v46, v46
	v_fmac_f32_e32 v41, v40, v40
	v_add_f32_e32 v38, v45, v39
	v_add_f32_e32 v39, v47, v41
	v_add_f32_e32 v44, v38, v39
	global_store_dwordx4 v[42:43], v[28:31], off
	v_lshlrev_b32_e32 v38, 16, v32
	v_and_b32_e32 v39, 0xffff0000, v32
	v_lshlrev_b32_e32 v32, 16, v33
	v_and_b32_e32 v33, 0xffff0000, v33
	v_lshlrev_b32_e32 v40, 16, v34
	v_and_b32_e32 v41, 0xffff0000, v34
	v_lshlrev_b32_e32 v34, 16, v35
	v_and_b32_e32 v35, 0xffff0000, v35
	v_pk_fma_f32 v[26:27], v[26:27], v[48:49], v[32:33] op_sel_hi:[1,0,1]
	v_pk_fma_f32 v[24:25], v[24:25], v[48:49], v[38:39] op_sel_hi:[1,0,1]
	v_pk_fma_f32 v[32:33], v[22:23], v[48:49], v[34:35] op_sel_hi:[1,0,1]
	v_pk_fma_f32 v[34:35], v[20:21], v[48:49], v[40:41] op_sel_hi:[1,0,1]
	v_mul_f32_e32 v20, v25, v25
	v_mul_f32_e32 v21, v27, v27
	v_mul_f32_e32 v22, v35, v35
	v_mul_f32_e32 v23, v33, v33
	v_fmac_f32_e32 v20, v24, v24
	v_fmac_f32_e32 v21, v26, v26
	v_fmac_f32_e32 v22, v34, v34
	v_fmac_f32_e32 v23, v32, v32
	v_add_f32_e32 v20, v20, v21
	v_add_f32_e32 v21, v22, v23
	v_add_f32_e32 v20, v20, v21
	v_add_f32_e32 v20, v44, v20
	ds_bpermute_b32 v21, v1, v20
	v_cvt_pk_bf16_f32 v22, v24, v25
	v_cvt_pk_bf16_f32 v23, v26, v27
	v_cvt_pk_bf16_f32 v24, v34, v35
	v_cvt_pk_bf16_f32 v25, v32, v33
	s_waitcnt lgkmcnt(0)
	v_add_f32_e32 v20, v20, v21
	ds_bpermute_b32 v21, v118, v20
	global_store_dwordx4 v[42:43], v[22:25], off offset:256
	s_and_saveexec_b64 s[0:1], s[40:41]
	s_cbranch_execz .LBB0_754
	v_lshl_add_u64 v[22:23], v[36:37], 2, s[44:45]
	s_waitcnt lgkmcnt(0)
	v_add_f32_e32 v20, v20, v21
	global_atomic_add_f32 v[22:23], v20, off
.LBB0_754:
	s_or_b64 exec, exec, s[0:1]
	s_nop 1
	v_mov_b32_e32 v28, v183
	v_add_u32_e32 v20, 0xb0, v150
	s_waitcnt lgkmcnt(0)
	v_ashrrev_i32_e32 v21, 31, v20
	v_lshlrev_b64 v[22:23], 11, v[20:21]
	v_lshl_add_u64 v[22:23], s[96:97], 0, v[22:23]
	v_lshl_add_u64 v[26:27], v[2:3], 1, v[22:23]
	global_load_dwordx4 v[22:25], v[26:27], off
	s_waitcnt vmcnt(1)
	v_fmamk_f32 v2, v28, 0x3b000000, v148
	v_mul_f32_e32 v3, 0x4f800000, v2
	v_cmp_gt_f32_e32 vcc, s63, v2
	s_waitcnt vmcnt(0)
	v_lshlrev_b32_e32 v28, 16, v24
	v_cndmask_b32_e32 v30, v2, v3, vcc
	v_sqrt_f32_e32 v31, v30
	v_lshlrev_b32_e32 v2, 16, v22
	v_and_b32_e32 v3, 0xffff0000, v22
	v_lshlrev_b32_e32 v22, 16, v23
	v_add_u32_e32 v32, -1, v31
	v_add_u32_e32 v33, 1, v31
	v_fma_f32 v34, -v32, v31, v30
	v_fma_f32 v35, -v33, v31, v30
	v_cmp_ge_f32_e64 s[0:1], 0, v34
	v_and_b32_e32 v23, 0xffff0000, v23
	v_and_b32_e32 v29, 0xffff0000, v24
	v_cndmask_b32_e64 v31, v31, v32, s[0:1]
	v_cmp_lt_f32_e64 s[0:1], 0, v35
	v_lshlrev_b32_e32 v24, 16, v25
	v_and_b32_e32 v25, 0xffff0000, v25
	v_cndmask_b32_e64 v31, v31, v33, s[0:1]
	v_mul_f32_e32 v32, 0x37800000, v31
	v_cndmask_b32_e32 v31, v31, v32, vcc
	v_cmp_class_f32_e32 vcc, v30, v162
	s_nop 1
	v_cndmask_b32_e32 v30, v31, v30, vcc
	v_div_scale_f32 v31, s[0:1], v30, v30, 1.0
	v_rcp_f32_e32 v32, v31
	v_div_scale_f32 v33, vcc, 1.0, v30, 1.0
	v_fma_f32 v34, -v31, v32, 1.0
	v_fmac_f32_e32 v32, v34, v32
	v_mul_f32_e32 v34, v33, v32
	v_fma_f32 v35, -v31, v34, v33
	v_fmac_f32_e32 v34, v35, v32
	v_fma_f32 v31, -v31, v34, v33
	v_div_fmas_f32 v31, v31, v32, v34
	v_div_fixup_f32 v30, v31, v30, 1.0
	v_pk_fma_f32 v[22:23], v[18:19], v[30:31], v[22:23] op_sel_hi:[1,0,1]
	v_pk_fma_f32 v[2:3], v[16:17], v[30:31], v[2:3] op_sel_hi:[1,0,1]
	v_pk_fma_f32 v[24:25], v[14:15], v[30:31], v[24:25] op_sel_hi:[1,0,1]
	v_pk_fma_f32 v[28:29], v[12:13], v[30:31], v[28:29] op_sel_hi:[1,0,1]
	v_cvt_pk_bf16_f32 v12, v2, v3
	v_cvt_pk_bf16_f32 v13, v22, v23
	v_mul_f32_e32 v3, v3, v3
	v_cvt_pk_bf16_f32 v14, v28, v29
	v_cvt_pk_bf16_f32 v15, v24, v25
	global_load_dwordx4 v[16:19], v[26:27], off offset:256
	v_mul_f32_e32 v23, v23, v23
	v_mul_f32_e32 v29, v29, v29
	v_mul_f32_e32 v25, v25, v25
	v_fmac_f32_e32 v3, v2, v2
	v_fmac_f32_e32 v23, v22, v22
	v_fmac_f32_e32 v29, v28, v28
	v_fmac_f32_e32 v25, v24, v24
	v_add_f32_e32 v2, v3, v23
	v_add_f32_e32 v3, v29, v25
	v_add_f32_e32 v24, v2, v3
	global_store_dwordx4 v[26:27], v[12:15], off
	s_waitcnt vmcnt(1)
	v_lshlrev_b32_e32 v2, 16, v16
	v_and_b32_e32 v3, 0xffff0000, v16
	v_lshlrev_b32_e32 v16, 16, v17
	v_and_b32_e32 v17, 0xffff0000, v17
	v_lshlrev_b32_e32 v22, 16, v18
	v_and_b32_e32 v23, 0xffff0000, v18
	v_lshlrev_b32_e32 v18, 16, v19
	v_and_b32_e32 v19, 0xffff0000, v19
	v_pk_fma_f32 v[10:11], v[10:11], v[30:31], v[16:17] op_sel_hi:[1,0,1]
	v_pk_fma_f32 v[2:3], v[8:9], v[30:31], v[2:3] op_sel_hi:[1,0,1]
	v_pk_fma_f32 v[8:9], v[6:7], v[30:31], v[18:19] op_sel_hi:[1,0,1]
	v_pk_fma_f32 v[6:7], v[4:5], v[30:31], v[22:23] op_sel_hi:[1,0,1]
	v_mul_f32_e32 v4, v3, v3
	v_mul_f32_e32 v5, v11, v11
	v_mul_f32_e32 v16, v7, v7
	v_mul_f32_e32 v17, v9, v9
	v_fmac_f32_e32 v4, v2, v2
	v_fmac_f32_e32 v5, v10, v10
	v_fmac_f32_e32 v16, v6, v6
	v_fmac_f32_e32 v17, v8, v8
	v_add_f32_e32 v4, v4, v5
	v_add_f32_e32 v5, v16, v17
	v_add_f32_e32 v4, v4, v5
	v_add_f32_e32 v5, v24, v4
	ds_bpermute_b32 v1, v1, v5
	v_cvt_pk_bf16_f32 v4, v2, v3
	s_waitcnt lgkmcnt(0)
	v_add_f32_e32 v1, v5, v1
	ds_bpermute_b32 v2, v118, v1
	v_cvt_pk_bf16_f32 v5, v10, v11
	v_cvt_pk_bf16_f32 v6, v6, v7
	v_cvt_pk_bf16_f32 v7, v8, v9
	global_store_dwordx4 v[26:27], v[4:7], off offset:256
	s_and_saveexec_b64 s[0:1], s[40:41]
	s_cbranch_execz .LBB0_756
	v_lshl_add_u64 v[4:5], v[20:21], 2, s[44:45]
	s_waitcnt lgkmcnt(0)
	v_add_f32_e32 v1, v1, v2
	global_atomic_add_f32 v[4:5], v1, off
